# baseline (speedup 1.0000x reference)
; __device__ __forceinline__ unsigned xb_add(unsigned* p, unsigned v) { return __hip_atomic_fetch_add(p, v, __ATOMIC_RELAXED, __HIP_MEMORY_SCOPE_AGENT); }
.Lxl_skip_gu:
	v_mov_b32_e32 v0, 1
	v_mov_b32_e32 v2, 0x2000
	global_atomic_add v2, v0, s[8:9] offset:1024
	buffer_inv sc1
	s_waitcnt vmcnt(0)
	s_branch .LBB0_362

; __device__ __forceinline__ unsigned xb_add(unsigned* p, unsigned v) { return __hip_atomic_fetch_add(p, v, __ATOMIC_RELAXED, __HIP_MEMORY_SCOPE_AGENT); }
.Lxl_skip_d:
	v_mov_b32_e32 v0, 1
	v_mov_b32_e32 v2, 0x2000
	global_atomic_add v2, v0, s[10:11] offset:1024
	buffer_inv sc1
	s_waitcnt vmcnt(0)
	s_branch .LBB0_455
